# plus: packed f32 bias adds in A near-band blocks and D loop split into scalar f32 adds
# baseline (speedup 1.0000x reference)
; template <int M>
; __device__ __forceinline__ void qkt_map_roll(f32x16& p0, f32x16& p1, int kb, int qa) {
;   p0 = f32x16{}; p1 = f32x16{};
;   const int a0 = kb ^ ((M << 7) | (0 << 5)); const bf16x8 x0 = lds_rd128<0>(a0), y0 = lds_rd128<8192>(a0); const bf16x8 z0 = (M == 0) ? lds_rd128<0>(qa) : lds_rd128<4096>(qa);
;   const int a1 = kb ^ ((M << 7) | (1 << 5)); const bf16x8 x1 = lds_rd128<0>(a1), y1 = lds_rd128<8192>(a1); const bf16x8 z1 = (M == 0) ? lds_rd128<1024>(qa) : lds_rd128<5120>(qa);
;   asm volatile("s_waitcnt lgkmcnt(3)" ::: "memory"); SBAR();
;   p0 = __builtin_amdgcn_mfma_f32_32x32x16_bf16(x0, z0, p0, 0, 0, 0); p1 = __builtin_amdgcn_mfma_f32_32x32x16_bf16(y0, z0, p1, 0, 0, 0);
;   const int a2 = kb ^ ((M << 7) | (2 << 5)); const bf16x8 x2 = lds_rd128<0>(a2), y2 = lds_rd128<8192>(a2); const bf16x8 z2 = (M == 0) ? lds_rd128<2048>(qa) : lds_rd128<6144>(qa);
;   asm volatile("s_waitcnt lgkmcnt(3)" ::: "memory"); SBAR();
;   p0 = __builtin_amdgcn_mfma_f32_32x32x16_bf16(x1, z1, p0, 0, 0, 0); p1 = __builtin_amdgcn_mfma_f32_32x32x16_bf16(y1, z1, p1, 0, 0, 0);
;   const int a3 = kb ^ ((M << 7) | (3 << 5)); const bf16x8 x3 = lds_rd128<0>(a3), y3 = lds_rd128<8192>(a3); const bf16x8 z3 = (M == 0) ? lds_rd128<3072>(qa) : lds_rd128<7168>(qa);
;   asm volatile("s_waitcnt lgkmcnt(3)" ::: "memory"); SBAR();
;   p0 = __builtin_amdgcn_mfma_f32_32x32x16_bf16(x2, z2, p0, 0, 0, 0); p1 = __builtin_amdgcn_mfma_f32_32x32x16_bf16(y2, z2, p1, 0, 0, 0);
;   asm volatile("s_waitcnt lgkmcnt(0)" ::: "memory"); SBAR();
;   p0 = __builtin_amdgcn_mfma_f32_32x32x16_bf16(x3, z3, p0, 0, 0, 0); p1 = __builtin_amdgcn_mfma_f32_32x32x16_bf16(y3, z3, p1, 0, 0, 0);
;   SBAR();
; __device__ __forceinline__ void attn_unit_A2(const bf16_t* __restrict__ Qb, int ldq, const bf16_t* __restrict__ Kh, int ldk, const bf16_t* __restrict__ Vh, int ldv, int nkeys, int q0, ...
;     ...
;     const int b = j & 1, kt0 = j * KVBLK;
;     const int dlo_ = kt0 - q0 - 255, dhi_ = kt0 + 63 - q0;
;     float cb = 0.f; const bool nearb = !(dlo_ >= 1024) && !(dhi_ <= -1024);
;     if (dlo_ >= 1024) cb = cb_hi; else if (dhi_ <= -1024) cb = cb_lo;
;     const float* tb_ = tbl_l + (kt0 - qlane + TOFF + 4 * hi);
;     f32x16 s0, s1; bf16x8 pa0, pa1, pa2, pa3; float al0, al1;
;     const int vb = vb0 + b * (int)SHM_V;
;     qkt_map_roll<0>(s0, s1, kbA + b * SHM_K, qaA);
;     SBAR();
;     if (nearb) {
; #pragma unroll
.LBB0_335:
	s_add_i32 s6, s61, s11
	s_cmp_lt_i32 s11, s60
	s_cselect_b64 s[8:9], -1, 0
	s_cmpk_gt_i32 s6, 0xfbc1
	s_cselect_b64 s[22:23], -1, 0
	s_and_b32 s64, s62, 0x4000
	v_add_u32_e32 v226, s64, v211
	ds_read_b128 v[2:5], v226 offset:0
	ds_read_b128 v[6:9], v226 offset:0x2000
	ds_read_b128 v[10:13], v208 offset:0
	v_xor_b32_e32 v144, 32, v226
	ds_read_b128 v[228:231], v144 offset:0
	ds_read_b128 v[232:235], v144 offset:0x2000
	ds_read_b128 v[236:239], v208 offset:0x400
	s_waitcnt lgkmcnt(3)
	s_and_b64 s[76:77], s[8:9], s[22:23]
	v_mfma_f32_32x32x16_bf16 v[160:175], v[2:5], v[10:13], 0
	v_mfma_f32_32x32x16_bf16 v[144:159], v[6:9], v[10:13], 0
	v_xor_b32_e32 v10, 64, v226
	ds_read_b128 v[2:5], v10 offset:0
	ds_read_b128 v[6:9], v10 offset:0x2000
	ds_read_b128 v[10:13], v208 offset:0x800
	s_waitcnt lgkmcnt(3)
	v_mfma_f32_32x32x16_bf16 v[160:175], v[228:231], v[236:239], v[160:175]
	v_xor_b32_e32 v192, 0x60, v226
	ds_read_b128 v[228:231], v192 offset:0
	v_mfma_f32_32x32x16_bf16 v[144:159], v[232:235], v[236:239], v[144:159]
	ds_read_b128 v[232:235], v192 offset:0x2000
	ds_read_b128 v[236:239], v208 offset:0xc00
	s_waitcnt lgkmcnt(3)
	v_mfma_f32_32x32x16_bf16 v[160:175], v[2:5], v[10:13], v[160:175]
	s_waitcnt lgkmcnt(0)
	v_mfma_f32_32x32x16_bf16 v[144:159], v[6:9], v[10:13], v[144:159]
	v_mfma_f32_32x32x16_bf16 v[160:175], v[228:231], v[236:239], v[160:175]
	v_mfma_f32_32x32x16_bf16 v[144:159], v[232:235], v[236:239], v[144:159]
	v_cndmask_b32_e64 v2, 0, 1, s[76:77]
	v_cmp_ne_u32_e64 s[6:7], 1, v2
	s_andn2_b64 vcc, exec, s[76:77]
	s_cbranch_vccnz .LBB0_337
	v_add_u32_e32 v15, s63, v217
	v_add_u32_e32 v223, 0x15e00, v15
	v_add_u32_e32 v234, 0x15e80, v15
	v_add_u32_e32 v235, 0x15e08, v15
	v_add_u32_e32 v236, 0x15e88, v15
	v_add_u32_e32 v237, 0x15e20, v15
	v_add_u32_e32 v238, 0x15ea0, v15
	v_add_u32_e32 v239, 0x15e28, v15
	v_add_u32_e32 v240, 0x15ea8, v15
	v_add_u32_e32 v228, 0x15e40, v15
	v_add_u32_e32 v229, 0x15ec0, v15
	v_add_u32_e32 v230, 0x15e48, v15
	v_add_u32_e32 v231, 0x15ec8, v15
	v_add_u32_e32 v232, 0x15e60, v15
	v_add_u32_e32 v224, 0x15ee0, v15
	v_add_u32_e32 v233, 0x15e68, v15
	v_add_u32_e32 v225, 0x15ee8, v15
	ds_read2_b32 v[2:3], v223 offset1:1
	ds_read2_b32 v[4:5], v234 offset1:1
	ds_read2_b32 v[6:7], v235 offset1:1
	ds_read2_b32 v[8:9], v236 offset1:1
	ds_read2_b32 v[10:11], v237 offset1:1
	ds_read2_b32 v[12:13], v238 offset1:1
	ds_read2_b32 v[192:193], v239 offset1:1
	ds_read2_b32 v[194:195], v240 offset1:1
	ds_read2_b32 v[202:203], v228 offset1:1
	ds_read2_b32 v[204:205], v229 offset1:1
	ds_read2_b32 v[220:221], v230 offset1:1
	ds_read2_b32 v[242:243], v231 offset1:1
	ds_read2_b32 v[244:245], v232 offset1:1
	ds_read2_b32 v[246:247], v233 offset1:1
	s_waitcnt lgkmcnt(9)
	v_add_f32_e32 v164, v164, v10
	v_add_f32_e32 v165, v165, v11
	v_add_f32_e32 v162, v162, v6
	v_add_f32_e32 v163, v163, v7
	ds_read2_b32 v[6:7], v225 offset1:1
	ds_read2_b32 v[10:11], v224 offset1:1
	s_waitcnt lgkmcnt(9)
	v_add_f32_e32 v166, v166, v192
	v_add_f32_e32 v167, v167, v193
	s_waitcnt lgkmcnt(2)
	v_add_f32_e32 v174, v174, v246
	v_add_f32_e32 v175, v175, v247
	v_add_f32_e32 v172, v172, v244
	v_add_f32_e32 v173, v173, v245
	v_add_f32_e32 v170, v170, v220
	v_add_f32_e32 v171, v171, v221
	v_add_f32_e32 v168, v168, v202
	v_add_f32_e32 v169, v169, v203
	v_add_f32_e32 v160, v160, v2
	v_add_f32_e32 v161, v161, v3
	v_add_f32_e32 v150, v150, v194
	v_add_f32_e32 v151, v151, v195
	v_add_f32_e32 v148, v148, v12
	v_add_f32_e32 v149, v149, v13
	v_add_f32_e32 v146, v146, v8
	v_add_f32_e32 v147, v147, v9
	s_waitcnt lgkmcnt(1)
	v_add_f32_e32 v158, v158, v6
	v_add_f32_e32 v159, v159, v7
	s_waitcnt lgkmcnt(0)
	v_add_f32_e32 v156, v156, v10
	v_add_f32_e32 v157, v157, v11
	v_add_f32_e32 v154, v154, v242
	v_add_f32_e32 v155, v155, v243
	v_add_f32_e32 v152, v152, v204
	v_add_f32_e32 v153, v153, v205
	v_add_f32_e32 v144, v144, v4
	v_add_f32_e32 v145, v145, v5

; #define SBAR() __builtin_amdgcn_sched_barrier(0)
; template <int M>
; __device__ __forceinline__ void qkt_map_roll(f32x16& p0, f32x16& p1, int kb, int qa) {
;   p0 = f32x16{}; p1 = f32x16{};
;   const int a0 = kb ^ ((M << 7) | (0 << 5)); const bf16x8 x0 = lds_rd128<0>(a0), y0 = lds_rd128<8192>(a0); const bf16x8 z0 = (M == 0) ? lds_rd128<0>(qa) : lds_rd128<4096>(qa);
;   const int a1 = kb ^ ((M << 7) | (1 << 5)); const bf16x8 x1 = lds_rd128<0>(a1), y1 = lds_rd128<8192>(a1); const bf16x8 z1 = (M == 0) ? lds_rd128<1024>(qa) : lds_rd128<5120>(qa);
;   asm volatile("s_waitcnt lgkmcnt(3)" ::: "memory"); SBAR();
;   p0 = __builtin_amdgcn_mfma_f32_32x32x16_bf16(x0, z0, p0, 0, 0, 0); p1 = __builtin_amdgcn_mfma_f32_32x32x16_bf16(y0, z0, p1, 0, 0, 0);
;   const int a2 = kb ^ ((M << 7) | (2 << 5)); const bf16x8 x2 = lds_rd128<0>(a2), y2 = lds_rd128<8192>(a2); const bf16x8 z2 = (M == 0) ? lds_rd128<2048>(qa) : lds_rd128<6144>(qa);
;   asm volatile("s_waitcnt lgkmcnt(3)" ::: "memory"); SBAR();
;   p0 = __builtin_amdgcn_mfma_f32_32x32x16_bf16(x1, z1, p0, 0, 0, 0); p1 = __builtin_amdgcn_mfma_f32_32x32x16_bf16(y1, z1, p1, 0, 0, 0);
;   const int a3 = kb ^ ((M << 7) | (3 << 5)); const bf16x8 x3 = lds_rd128<0>(a3), y3 = lds_rd128<8192>(a3); const bf16x8 z3 = (M == 0) ? lds_rd128<3072>(qa) : lds_rd128<7168>(qa);
;   asm volatile("s_waitcnt lgkmcnt(3)" ::: "memory"); SBAR();
;   p0 = __builtin_amdgcn_mfma_f32_32x32x16_bf16(x2, z2, p0, 0, 0, 0); p1 = __builtin_amdgcn_mfma_f32_32x32x16_bf16(y2, z2, p1, 0, 0, 0);
;   asm volatile("s_waitcnt lgkmcnt(0)" ::: "memory"); SBAR();
;   p0 = __builtin_amdgcn_mfma_f32_32x32x16_bf16(x3, z3, p0, 0, 0, 0); p1 = __builtin_amdgcn_mfma_f32_32x32x16_bf16(y3, z3, p1, 0, 0, 0);
;   SBAR();
; __device__ __forceinline__ void attn_unit_A2(const bf16_t* __restrict__ Qb, int ldq, const bf16_t* __restrict__ Kh, int ldk, const bf16_t* __restrict__ Vh, int ldv, int nkeys, int q0, ...
;     ...
;     pv_d0(oa, vb, pa0, pa1, pa2, pa3);
;     SBAR();
;     qkt_map_roll<1>(s0, s1, kbA + b * SHM_K, qaA);
;     SBAR();
;     if (nearb) {
; #pragma unroll
;       for (int r = 0; r < 8; ++r) { s0[r] += tb_[(r & 3) + 8 * (r >> 2)]; s1[r] += tb_[32 + (r & 3) + 8 * (r >> 2)]; }
;       SBAR();
; #pragma unroll
;       for (int r = 8; r < 16; ++r) { s0[r] += tb_[(r & 3) + 8 * (r >> 2)]; s1[r] += tb_[32 + (r & 3) + 8 * (r >> 2)]; } }
.LBB0_341:
	v_add_u32_e32 v222, s64, v214
	ds_read_b64_tr_b16 v[148:149], v222 offset:0
	ds_read_b64_tr_b16 v[150:151], v222 offset:0x800
	ds_read_b64_tr_b16 v[152:153], v222 offset:0x1000
	ds_read_b64_tr_b16 v[154:155], v222 offset:0x1800
	ds_read_b64_tr_b16 v[156:157], v222 offset:0x2000
	ds_read_b64_tr_b16 v[158:159], v222 offset:0x2800
	ds_read_b64_tr_b16 v[160:161], v222 offset:0x3000
	ds_read_b64_tr_b16 v[162:163], v222 offset:0x3800
	ds_read_b64_tr_b16 v[164:165], v222 offset:0x200
	ds_read_b64_tr_b16 v[166:167], v222 offset:0xa00
	s_waitcnt lgkmcnt(8)
	s_nop 0
	v_mfma_f32_32x32x16_bf16 v[128:143], v[2:5], v[148:151], v[128:143]
	ds_read_b64_tr_b16 v[148:149], v222 offset:0x1200
	ds_read_b64_tr_b16 v[150:151], v222 offset:0x1a00
	s_waitcnt lgkmcnt(8)
	v_mfma_f32_32x32x16_bf16 v[128:143], v[6:9], v[152:155], v[128:143]
	ds_read_b64_tr_b16 v[152:153], v222 offset:0x2200
	ds_read_b64_tr_b16 v[154:155], v222 offset:0x2a00
	s_waitcnt lgkmcnt(8)
	v_mfma_f32_32x32x16_bf16 v[128:143], v[10:13], v[156:159], v[128:143]
	ds_read_b64_tr_b16 v[156:157], v222 offset:0x3200
	ds_read_b64_tr_b16 v[158:159], v222 offset:0x3a00
	s_waitcnt lgkmcnt(8)
	v_mfma_f32_32x32x16_bf16 v[128:143], v[144:147], v[160:163], v[128:143]
	ds_read_b64_tr_b16 v[160:161], v222 offset:0x400
	ds_read_b64_tr_b16 v[162:163], v222 offset:0xc00
	s_waitcnt lgkmcnt(8)
	v_mfma_f32_32x32x16_bf16 v[96:111], v[2:5], v[164:167], v[96:111]
	ds_read_b64_tr_b16 v[164:165], v222 offset:0x1400
	ds_read_b64_tr_b16 v[166:167], v222 offset:0x1c00
	s_waitcnt lgkmcnt(8)
	v_mfma_f32_32x32x16_bf16 v[96:111], v[6:9], v[148:151], v[96:111]
	ds_read_b64_tr_b16 v[148:149], v222 offset:0x2400
	ds_read_b64_tr_b16 v[150:151], v222 offset:0x2c00
	s_waitcnt lgkmcnt(8)
	v_mfma_f32_32x32x16_bf16 v[96:111], v[10:13], v[152:155], v[96:111]
	ds_read_b64_tr_b16 v[152:153], v222 offset:0x3400
	ds_read_b64_tr_b16 v[154:155], v222 offset:0x3c00
	s_waitcnt lgkmcnt(8)
	v_mfma_f32_32x32x16_bf16 v[96:111], v[144:147], v[156:159], v[96:111]
	ds_read_b64_tr_b16 v[156:157], v222 offset:0x600
	ds_read_b64_tr_b16 v[158:159], v222 offset:0xe00
	s_waitcnt lgkmcnt(8)
	v_mfma_f32_32x32x16_bf16 v[48:63], v[2:5], v[160:163], v[48:63]
	ds_read_b64_tr_b16 v[160:161], v222 offset:0x1600
	ds_read_b64_tr_b16 v[162:163], v222 offset:0x1e00
	s_waitcnt lgkmcnt(8)
	v_mfma_f32_32x32x16_bf16 v[48:63], v[6:9], v[164:167], v[48:63]
	ds_read_b64_tr_b16 v[164:165], v222 offset:0x2600
	ds_read_b64_tr_b16 v[166:167], v222 offset:0x2e00
	s_waitcnt lgkmcnt(8)
	v_mfma_f32_32x32x16_bf16 v[48:63], v[10:13], v[148:151], v[48:63]
	ds_read_b64_tr_b16 v[148:149], v222 offset:0x3600
	ds_read_b64_tr_b16 v[150:151], v222 offset:0x3e00
	s_waitcnt lgkmcnt(8)
	v_mfma_f32_32x32x16_bf16 v[48:63], v[144:147], v[152:155], v[48:63]
	s_waitcnt lgkmcnt(6)
	v_mfma_f32_32x32x16_bf16 v[80:95], v[2:5], v[156:159], v[80:95]
	s_waitcnt lgkmcnt(4)
	v_mfma_f32_32x32x16_bf16 v[80:95], v[6:9], v[160:163], v[80:95]
	s_waitcnt lgkmcnt(2)
	v_mfma_f32_32x32x16_bf16 v[80:95], v[10:13], v[164:167], v[80:95]
	s_waitcnt lgkmcnt(0)
	v_mfma_f32_32x32x16_bf16 v[80:95], v[144:147], v[148:151], v[80:95]
	v_xor_b32_e32 v10, 0x80, v226
	ds_read_b128 v[2:5], v10 offset:0
	ds_read_b128 v[6:9], v10 offset:0x2000
	ds_read_b128 v[10:13], v208 offset:0x1000
	v_xor_b32_e32 v144, 0xa0, v226
	ds_read_b128 v[242:245], v144 offset:0
	ds_read_b128 v[246:249], v144 offset:0x2000
	ds_read_b128 v[250:253], v208 offset:0x1400
	s_waitcnt lgkmcnt(3)
	s_nop 0
	v_mfma_f32_32x32x16_bf16 v[160:175], v[2:5], v[10:13], 0
	v_mfma_f32_32x32x16_bf16 v[144:159], v[6:9], v[10:13], 0
	v_xor_b32_e32 v10, 0xc0, v226
	ds_read_b128 v[2:5], v10 offset:0
	ds_read_b128 v[6:9], v10 offset:0x2000
	ds_read_b128 v[10:13], v208 offset:0x1800
	s_waitcnt lgkmcnt(3)
	v_mfma_f32_32x32x16_bf16 v[160:175], v[242:245], v[250:253], v[160:175]
	v_xor_b32_e32 v192, 0xe0, v226
	ds_read_b128 v[242:245], v192 offset:0
	v_mfma_f32_32x32x16_bf16 v[144:159], v[246:249], v[250:253], v[144:159]
	ds_read_b128 v[246:249], v192 offset:0x2000
	ds_read_b128 v[250:253], v208 offset:0x1c00
	s_waitcnt lgkmcnt(3)
	v_mfma_f32_32x32x16_bf16 v[160:175], v[2:5], v[10:13], v[160:175]
	s_waitcnt lgkmcnt(0)
	v_mfma_f32_32x32x16_bf16 v[144:159], v[6:9], v[10:13], v[144:159]
	v_mfma_f32_32x32x16_bf16 v[160:175], v[242:245], v[250:253], v[160:175]
	v_mfma_f32_32x32x16_bf16 v[144:159], v[246:249], v[250:253], v[144:159]
	s_and_b64 vcc, exec, s[6:7]
	s_cbranch_vccnz .LBB0_343
	ds_read2_b32 v[2:3], v223 offset1:1
	ds_read2_b32 v[4:5], v234 offset1:1
	ds_read2_b32 v[6:7], v235 offset1:1
	ds_read2_b32 v[8:9], v236 offset1:1
	ds_read2_b32 v[10:11], v237 offset1:1
	ds_read2_b32 v[12:13], v238 offset1:1
	ds_read2_b32 v[192:193], v239 offset1:1
	ds_read2_b32 v[194:195], v240 offset1:1
	ds_read2_b32 v[202:203], v228 offset1:1
	ds_read2_b32 v[204:205], v229 offset1:1
	ds_read2_b32 v[228:229], v230 offset1:1
	ds_read2_b32 v[230:231], v231 offset1:1
	ds_read2_b32 v[234:235], v232 offset1:1
	ds_read2_b32 v[232:233], v233 offset1:1
	s_waitcnt lgkmcnt(9)
	v_add_f32_e32 v164, v164, v10
	v_add_f32_e32 v165, v165, v11
	v_add_f32_e32 v162, v162, v6
	v_add_f32_e32 v163, v163, v7
	ds_read2_b32 v[6:7], v225 offset1:1
	ds_read2_b32 v[10:11], v224 offset1:1
	s_waitcnt lgkmcnt(9)
	v_add_f32_e32 v166, v166, v192
	v_add_f32_e32 v167, v167, v193
	s_waitcnt lgkmcnt(2)
	v_add_f32_e32 v174, v174, v232
	v_add_f32_e32 v175, v175, v233
	v_add_f32_e32 v172, v172, v234
	v_add_f32_e32 v173, v173, v235
	v_add_f32_e32 v170, v170, v228
	v_add_f32_e32 v171, v171, v229
	v_add_f32_e32 v168, v168, v202
	v_add_f32_e32 v169, v169, v203
	v_add_f32_e32 v160, v160, v2
	v_add_f32_e32 v161, v161, v3
	v_add_f32_e32 v150, v150, v194
	v_add_f32_e32 v151, v151, v195
	v_add_f32_e32 v148, v148, v12
	v_add_f32_e32 v149, v149, v13
	v_add_f32_e32 v146, v146, v8
	v_add_f32_e32 v147, v147, v9
	s_waitcnt lgkmcnt(1)
	v_add_f32_e32 v158, v158, v6
	v_add_f32_e32 v159, v159, v7
	s_waitcnt lgkmcnt(0)
	v_add_f32_e32 v156, v156, v10
	v_add_f32_e32 v157, v157, v11
	v_add_f32_e32 v154, v154, v230
	v_add_f32_e32 v155, v155, v231
	v_add_f32_e32 v152, v152, v204
	v_add_f32_e32 v153, v153, v205
	v_add_f32_e32 v144, v144, v4
	v_add_f32_e32 v145, v145, v5

; #define SBAR() __builtin_amdgcn_sched_barrier(0)
; __device__ __forceinline__ void qkt8_fsm(f32x16& p0, f32x16& p1, const f32x16& negm, int kb, const bf16x8* qr, f32x16& q0p, f32x16& q1p, float alpha, float& l_reg, bf16x8& pa0, bf16x8& pa1, bf16x8& pa2, bf16x8& pa3) {
;   float sm[4];
;   const int a0 = kb ^ (0 << 5); const bf16x8 x0 = lds_rd128<0>(a0), y0 = lds_rd128<8192>(a0);
;   const int a1 = kb ^ (1 << 5); const bf16x8 x1 = lds_rd128<0>(a1), y1 = lds_rd128<8192>(a1);
;   const int a2 = kb ^ (2 << 5); const bf16x8 x2 = lds_rd128<0>(a2), y2 = lds_rd128<8192>(a2);
;   asm volatile("s_waitcnt lgkmcnt(4)" ::: "memory"); SBAR();
;   p0 = __builtin_amdgcn_mfma_f32_32x32x16_bf16(x0, qr[0], negm, 0, 0, 0); p1 = __builtin_amdgcn_mfma_f32_32x32x16_bf16(y0, qr[0], negm, 0, 0, 0);
;   fsm_slice<0>(q0p, q1p, alpha, l_reg, pa0, pa1, pa2, pa3, sm); SBAR();
;   const int a3 = kb ^ (3 << 5); const bf16x8 x3 = lds_rd128<0>(a3), y3 = lds_rd128<8192>(a3);
;   asm volatile("s_waitcnt lgkmcnt(4)" ::: "memory"); SBAR();
;   p0 = __builtin_amdgcn_mfma_f32_32x32x16_bf16(x1, qr[1], p0, 0, 0, 0); p1 = __builtin_amdgcn_mfma_f32_32x32x16_bf16(y1, qr[1], p1, 0, 0, 0);
;   fsm_slice<1>(q0p, q1p, alpha, l_reg, pa0, pa1, pa2, pa3, sm); SBAR();
;   const int a4 = kb ^ (4 << 5); const bf16x8 x4 = lds_rd128<0>(a4), y4 = lds_rd128<8192>(a4);
;   asm volatile("s_waitcnt lgkmcnt(4)" ::: "memory"); SBAR();
;   p0 = __builtin_amdgcn_mfma_f32_32x32x16_bf16(x2, qr[2], p0, 0, 0, 0); p1 = __builtin_amdgcn_mfma_f32_32x32x16_bf16(y2, qr[2], p1, 0, 0, 0);
;   fsm_slice<2>(q0p, q1p, alpha, l_reg, pa0, pa1, pa2, pa3, sm); SBAR();
;   const int a5 = kb ^ (5 << 5); const bf16x8 x5 = lds_rd128<0>(a5), y5 = lds_rd128<8192>(a5);
;   asm volatile("s_waitcnt lgkmcnt(4)" ::: "memory"); SBAR();
;   p0 = __builtin_amdgcn_mfma_f32_32x32x16_bf16(x3, qr[3], p0, 0, 0, 0); p1 = __builtin_amdgcn_mfma_f32_32x32x16_bf16(y3, qr[3], p1, 0, 0, 0);
;   fsm_slice<3>(q0p, q1p, alpha, l_reg, pa0, pa1, pa2, pa3, sm); SBAR();
;   const int a6 = kb ^ (6 << 5); const bf16x8 x6 = lds_rd128<0>(a6), y6 = lds_rd128<8192>(a6);
;   asm volatile("s_waitcnt lgkmcnt(4)" ::: "memory"); SBAR();
;   p0 = __builtin_amdgcn_mfma_f32_32x32x16_bf16(x4, qr[4], p0, 0, 0, 0); p1 = __builtin_amdgcn_mfma_f32_32x32x16_bf16(y4, qr[4], p1, 0, 0, 0);
;   fsm_slice<4>(q0p, q1p, alpha, l_reg, pa0, pa1, pa2, pa3, sm); SBAR();
.LBB0_486:
	s_add_i32 s46, s44, s45
	s_cmp_gt_i32 s45, s11
	s_cselect_b64 s[6:7], -1, 0
	s_cmpk_lt_i32 s46, 0xfbc2
	s_cselect_b64 s[8:9], -1, 0
	v_sub_f32_e32 v82, 0, v222
	s_or_b64 s[8:9], s[6:7], s[8:9]
	v_cndmask_b32_e64 v243, -v222, v82, s[8:9]
	v_cmp_neq_f32_e32 vcc, v243, v241
	s_cmp_eq_u64 vcc, 0
	s_cselect_b64 s[6:7], -1, 0
	v_cndmask_b32_e64 v81, v243, v81, s[6:7]
	v_cndmask_b32_e64 v80, v243, v80, s[6:7]
	v_cndmask_b32_e64 v79, v243, v79, s[6:7]
	v_cndmask_b32_e64 v78, v243, v78, s[6:7]
	v_cndmask_b32_e64 v77, v243, v77, s[6:7]
	v_cndmask_b32_e64 v76, v243, v76, s[6:7]
	v_cndmask_b32_e64 v75, v243, v75, s[6:7]
	v_cndmask_b32_e64 v74, v243, v74, s[6:7]
	v_cndmask_b32_e64 v73, v243, v73, s[6:7]
	v_cndmask_b32_e64 v72, v243, v72, s[6:7]
	v_cndmask_b32_e64 v71, v243, v71, s[6:7]
	v_cndmask_b32_e64 v70, v243, v70, s[6:7]
	v_cndmask_b32_e64 v69, v243, v69, s[6:7]
	v_cndmask_b32_e64 v68, v243, v68, s[6:7]
	v_cndmask_b32_e64 v67, v243, v67, s[6:7]
	v_cndmask_b32_e64 v66, v243, v66, s[6:7]
	ds_read_b128 v[82:85], v233 offset:0
	ds_read_b128 v[178:181], v233 offset:0x2000
	ds_read_b128 v[182:185], v232 offset:0
	ds_read_b128 v[186:189], v232 offset:0x2000
	ds_read_b128 v[192:195], v231 offset:0
	ds_read_b128 v[244:247], v231 offset:0x2000
	s_waitcnt lgkmcnt(4)
	s_nop 1
	v_mfma_f32_32x32x16_bf16 v[98:113], v[82:85], v[142:145], v[66:81]
	v_mfma_f32_32x32x16_bf16 v[82:97], v[178:181], v[142:145], v[66:81]
	ds_read_b128 v[178:181], v230 offset:0
	ds_read_b128 v[248:251], v230 offset:0x2000
	s_waitcnt lgkmcnt(4)
	v_mfma_f32_32x32x16_bf16 v[98:113], v[182:185], v[138:141], v[98:113]
	v_mfma_f32_32x32x16_bf16 v[82:97], v[186:189], v[138:141], v[82:97]
	ds_read_b128 v[182:185], v229 offset:0
	ds_read_b128 v[186:189], v229 offset:0x2000
	s_waitcnt lgkmcnt(4)
	v_mfma_f32_32x32x16_bf16 v[98:113], v[192:195], v[134:137], v[98:113]
	v_add_f32_e32 v192, v146, v148
	v_add_f32_e32 v193, v177, v175
	v_add_f32_e32 v194, v147, v149
	v_add_f32_e32 v195, v176, v174
	v_add_f32_e32 v192, v150, v192
	v_add_f32_e32 v193, v173, v193
	v_add_f32_e32 v194, v151, v194
	v_mfma_f32_32x32x16_bf16 v[82:97], v[244:247], v[134:137], v[82:97]
	v_add_f32_e32 v195, v172, v195
	v_add_f32_e32 v202, v152, v192
	v_add_f32_e32 v203, v171, v193
	v_add_f32_e32 v204, v153, v194
	v_add_f32_e32 v205, v170, v195
	ds_read_b128 v[192:195], v228 offset:0
	ds_read_b128 v[244:247], v228 offset:0x2000
	s_waitcnt lgkmcnt(4)
	v_mfma_f32_32x32x16_bf16 v[98:113], v[178:181], v[130:133], v[98:113]
	v_add_f32_e32 v178, v154, v202
	v_add_f32_e32 v179, v169, v203
	v_add_f32_e32 v180, v155, v204
	v_add_f32_e32 v181, v168, v205
	v_add_f32_e32 v178, v156, v178
	v_add_f32_e32 v179, v167, v179
	v_add_f32_e32 v180, v157, v180
	v_mfma_f32_32x32x16_bf16 v[82:97], v[248:251], v[130:133], v[82:97]
	v_add_f32_e32 v181, v166, v181
	v_add_f32_e32 v178, v158, v178
	v_add_f32_e32 v179, v165, v179
	v_add_f32_e32 v180, v159, v180
	v_add_f32_e32 v181, v164, v181
	v_add_f32_e32 v202, v160, v178
	v_add_f32_e32 v203, v163, v179
	v_add_f32_e32 v204, v161, v180
	v_add_f32_e32 v205, v162, v181
	ds_read_b128 v[178:181], v227 offset:0
	ds_read_b128 v[248:251], v227 offset:0x2000
	s_waitcnt lgkmcnt(4)
	v_mfma_f32_32x32x16_bf16 v[98:113], v[182:185], v[126:129], v[98:113]
	v_add_f32_e32 v182, v202, v203
	v_add_f32_e32 v183, v204, v205
	v_add_f32_e32 v239, v182, v183
	v_mov_b32_e32 v240, v239
	v_cvt_pk_bf16_f32 v146, v146, v177
	v_cvt_pk_bf16_f32 v147, v147, v176
	v_cvt_pk_bf16_f32 v148, v148, v175
	v_mfma_f32_32x32x16_bf16 v[82:97], v[186:189], v[126:129], v[82:97]
	v_cvt_pk_bf16_f32 v149, v149, v174
	s_nop 0
	v_permlane32_swap_b32_e32 v239, v240
	v_permlane32_swap_b32_e32 v146, v148
	v_permlane32_swap_b32_e32 v147, v149
	ds_read_b128 v[174:177], v226 offset:0
	ds_read_b128 v[182:185], v226 offset:0x2000
	s_waitcnt lgkmcnt(4)
	v_mfma_f32_32x32x16_bf16 v[98:113], v[192:195], v[122:125], v[98:113]
	v_cvt_pk_bf16_f32 v150, v150, v173
	v_cvt_pk_bf16_f32 v151, v151, v172
	v_cvt_pk_bf16_f32 v152, v152, v171
	v_cvt_pk_bf16_f32 v153, v153, v170
	s_nop 0
	v_permlane32_swap_b32_e32 v150, v152
	v_mfma_f32_32x32x16_bf16 v[82:97], v[244:247], v[122:125], v[82:97]
	v_permlane32_swap_b32_e32 v151, v153
	s_waitcnt lgkmcnt(2)
	v_mfma_f32_32x32x16_bf16 v[98:113], v[178:181], v[118:121], v[98:113]
	v_cvt_pk_bf16_f32 v154, v154, v169
	v_cvt_pk_bf16_f32 v155, v155, v168
	v_cvt_pk_bf16_f32 v156, v156, v167
	v_cvt_pk_bf16_f32 v157, v157, v166
	s_nop 0
	v_permlane32_swap_b32_e32 v154, v156
	v_mfma_f32_32x32x16_bf16 v[82:97], v[248:251], v[118:121], v[82:97]
	v_permlane32_swap_b32_e32 v155, v157
	s_waitcnt lgkmcnt(0)
	v_mfma_f32_32x32x16_bf16 v[98:113], v[174:177], v[114:117], v[98:113]
	v_cvt_pk_bf16_f32 v158, v158, v165
	v_cvt_pk_bf16_f32 v159, v159, v164
	v_cvt_pk_bf16_f32 v160, v160, v163
	v_cvt_pk_bf16_f32 v161, v161, v162
	s_nop 0
	v_permlane32_swap_b32_e32 v158, v160
	v_mfma_f32_32x32x16_bf16 v[82:97], v[182:185], v[114:117], v[82:97]
	v_permlane32_swap_b32_e32 v159, v161
	v_add_u32_e32 v238, s45, v212
	v_add_u32_e32 v170, 64, v238
	v_add_u32_e32 v172, 0x60, v238
	v_mad_i64_i32 v[162:163], s[50:51], v170, s55, v[198:199]
	v_mad_i64_i32 v[166:167], s[50:51], v172, s55, v[198:199]
	v_mad_i64_i32 v[170:171], s[50:51], v170, s55, v[200:201]
	v_mad_i64_i32 v[174:175], s[50:51], v172, s55, v[200:201]
	global_load_dwordx4 v[162:165], v[162:163], off
	s_nop 0
	global_load_dwordx4 v[166:169], v[166:167], off
	s_nop 0
	global_load_dwordx4 v[170:173], v[170:171], off
	s_nop 0
	global_load_dwordx4 v[174:177], v[174:175], off
	s_and_b64 vcc, exec, s[8:9]
	s_cbranch_vccnz .LBB0_488
	ds_read2_b32 v[178:179], v236 offset1:1
	ds_read2_b32 v[180:181], v236 offset0:2 offset1:3
	ds_read2_b32 v[182:183], v236 offset0:8 offset1:9
	ds_read2_b32 v[184:185], v236 offset0:10 offset1:11
	ds_read2_b32 v[186:187], v236 offset0:16 offset1:17
	ds_read2_b32 v[188:189], v236 offset0:18 offset1:19
	ds_read2_b32 v[192:193], v236 offset0:24 offset1:25
	ds_read2_b32 v[194:195], v236 offset0:26 offset1:27
	ds_read2_b32 v[202:203], v236 offset0:32 offset1:33
	ds_read2_b32 v[204:205], v236 offset0:34 offset1:35
	ds_read2_b32 v[244:245], v236 offset0:40 offset1:41
	ds_read2_b32 v[246:247], v236 offset0:42 offset1:43
	s_waitcnt lgkmcnt(11)
	v_add_f32_e32 v98, v98, v178
	v_add_f32_e32 v99, v99, v179
	s_waitcnt lgkmcnt(5)
	v_add_f32_e32 v110, v110, v192
	v_add_f32_e32 v111, v111, v193
	v_add_f32_e32 v108, v108, v188
	v_add_f32_e32 v109, v109, v189
	v_add_f32_e32 v106, v106, v186
	v_add_f32_e32 v107, v107, v187
	ds_read2_b32 v[178:179], v236 offset0:48 offset1:49
	ds_read2_b32 v[186:187], v236 offset0:50 offset1:51
	ds_read2_b32 v[188:189], v236 offset0:56 offset1:57
	ds_read2_b32 v[192:193], v236 offset0:58 offset1:59
	s_waitcnt lgkmcnt(8)
	v_add_f32_e32 v112, v112, v194
	v_add_f32_e32 v113, v113, v195
	v_add_f32_e32 v104, v104, v184
	v_add_f32_e32 v105, v105, v185
	v_add_f32_e32 v102, v102, v182
	v_add_f32_e32 v103, v103, v183
	v_add_f32_e32 v100, v100, v180
	v_add_f32_e32 v101, v101, v181
	s_waitcnt lgkmcnt(7)
	v_add_f32_e32 v82, v82, v202
	v_add_f32_e32 v83, v83, v203
	s_waitcnt lgkmcnt(0)
	v_add_f32_e32 v96, v96, v192
	v_add_f32_e32 v97, v97, v193
	v_add_f32_e32 v94, v94, v188
	v_add_f32_e32 v95, v95, v189
	v_add_f32_e32 v92, v92, v186
	v_add_f32_e32 v93, v93, v187
	v_add_f32_e32 v90, v90, v178
	v_add_f32_e32 v91, v91, v179
	v_add_f32_e32 v88, v88, v246
	v_add_f32_e32 v89, v89, v247
	v_add_f32_e32 v86, v86, v244
	v_add_f32_e32 v87, v87, v245
	v_add_f32_e32 v84, v84, v204
	v_add_f32_e32 v85, v85, v205

; #define SBAR() __builtin_amdgcn_sched_barrier(0)
; __device__ __forceinline__ void qkt8_fsm(f32x16& p0, f32x16& p1, const f32x16& negm, int kb, const bf16x8* qr, f32x16& q0p, f32x16& q1p, float alpha, float& l_reg, bf16x8& pa0, bf16x8& pa1, bf16x8& pa2, bf16x8& pa3) {
;   float sm[4];
;   const int a0 = kb ^ (0 << 5); const bf16x8 x0 = lds_rd128<0>(a0), y0 = lds_rd128<8192>(a0);
;   const int a1 = kb ^ (1 << 5); const bf16x8 x1 = lds_rd128<0>(a1), y1 = lds_rd128<8192>(a1);
;   const int a2 = kb ^ (2 << 5); const bf16x8 x2 = lds_rd128<0>(a2), y2 = lds_rd128<8192>(a2);
;   asm volatile("s_waitcnt lgkmcnt(4)" ::: "memory"); SBAR();
;   p0 = __builtin_amdgcn_mfma_f32_32x32x16_bf16(x0, qr[0], negm, 0, 0, 0); p1 = __builtin_amdgcn_mfma_f32_32x32x16_bf16(y0, qr[0], negm, 0, 0, 0);
;   fsm_slice<0>(q0p, q1p, alpha, l_reg, pa0, pa1, pa2, pa3, sm); SBAR();
;   const int a3 = kb ^ (3 << 5); const bf16x8 x3 = lds_rd128<0>(a3), y3 = lds_rd128<8192>(a3);
;   asm volatile("s_waitcnt lgkmcnt(4)" ::: "memory"); SBAR();
;   p0 = __builtin_amdgcn_mfma_f32_32x32x16_bf16(x1, qr[1], p0, 0, 0, 0); p1 = __builtin_amdgcn_mfma_f32_32x32x16_bf16(y1, qr[1], p1, 0, 0, 0);
;   fsm_slice<1>(q0p, q1p, alpha, l_reg, pa0, pa1, pa2, pa3, sm); SBAR();
;   const int a4 = kb ^ (4 << 5); const bf16x8 x4 = lds_rd128<0>(a4), y4 = lds_rd128<8192>(a4);
;   asm volatile("s_waitcnt lgkmcnt(4)" ::: "memory"); SBAR();
;   p0 = __builtin_amdgcn_mfma_f32_32x32x16_bf16(x2, qr[2], p0, 0, 0, 0); p1 = __builtin_amdgcn_mfma_f32_32x32x16_bf16(y2, qr[2], p1, 0, 0, 0);
;   fsm_slice<2>(q0p, q1p, alpha, l_reg, pa0, pa1, pa2, pa3, sm); SBAR();
;   const int a5 = kb ^ (5 << 5); const bf16x8 x5 = lds_rd128<0>(a5), y5 = lds_rd128<8192>(a5);
;   asm volatile("s_waitcnt lgkmcnt(4)" ::: "memory"); SBAR();
;   p0 = __builtin_amdgcn_mfma_f32_32x32x16_bf16(x3, qr[3], p0, 0, 0, 0); p1 = __builtin_amdgcn_mfma_f32_32x32x16_bf16(y3, qr[3], p1, 0, 0, 0);
;   fsm_slice<3>(q0p, q1p, alpha, l_reg, pa0, pa1, pa2, pa3, sm); SBAR();
;   const int a6 = kb ^ (6 << 5); const bf16x8 x6 = lds_rd128<0>(a6), y6 = lds_rd128<8192>(a6);
;     ...
;     if constexpr (ORD == 0) {
;     NEGM_UPD(kbeg + (j + 1) * KVBLK); SBAR();
;     qkt8_fsm(pA0, pA1, negm, kb0, qr, pB0, pB1, alB, l_reg, pa0, pa1, pa2, pa3);
;     if (SDEPTH == 1 || j + 3 < NT) SLOAD(SE, kbeg + (j + 1 + SDEPTH) * KVBLK); SBAR();
;     BIASADD(pA0, pA1, kbeg + (j + 1) * KVBLK); SBAR();
.LBB0_493:
	v_cndmask_b32_e64 v241, v243, v241, s[6:7]
	s_add_i32 s6, s45, 64
	s_add_i32 s46, s46, 64
	s_cmp_gt_i32 s6, s11
	s_cselect_b64 s[6:7], -1, 0
	s_cmpk_lt_i32 s46, 0xfbc2
	s_cselect_b64 s[8:9], -1, 0
	v_exp_f32_e32 v154, v82
	v_sub_f32_e32 v82, 0, v222
	s_or_b64 s[8:9], s[6:7], s[8:9]
	v_cndmask_b32_e64 v243, -v222, v82, s[8:9]
	v_exp_f32_e32 v146, v98
	v_exp_f32_e32 v177, v99
	v_exp_f32_e32 v147, v100
	v_exp_f32_e32 v176, v101
	v_exp_f32_e32 v148, v102
	v_exp_f32_e32 v175, v103
	v_exp_f32_e32 v149, v104
	v_exp_f32_e32 v174, v105
	v_exp_f32_e32 v150, v106
	v_exp_f32_e32 v173, v107
	v_exp_f32_e32 v151, v108
	v_exp_f32_e32 v172, v109
	v_exp_f32_e32 v152, v110
	v_exp_f32_e32 v171, v111
	v_exp_f32_e32 v153, v112
	v_exp_f32_e32 v170, v113
	v_exp_f32_e32 v169, v83
	v_exp_f32_e32 v155, v84
	v_exp_f32_e32 v168, v85
	v_exp_f32_e32 v156, v86
	v_exp_f32_e32 v167, v87
	v_exp_f32_e32 v157, v88
	v_exp_f32_e32 v166, v89
	v_exp_f32_e32 v158, v90
	v_exp_f32_e32 v165, v91
	v_exp_f32_e32 v159, v92
	v_exp_f32_e32 v164, v93
	v_exp_f32_e32 v160, v94
	v_exp_f32_e32 v163, v95
	v_exp_f32_e32 v161, v96
	v_exp_f32_e32 v162, v97
	v_cmp_neq_f32_e32 vcc, v243, v241
	s_cmp_eq_u64 vcc, 0
	s_cselect_b64 s[6:7], -1, 0
	v_cndmask_b32_e64 v81, v243, v81, s[6:7]
	v_cndmask_b32_e64 v80, v243, v80, s[6:7]
	v_cndmask_b32_e64 v79, v243, v79, s[6:7]
	v_cndmask_b32_e64 v78, v243, v78, s[6:7]
	v_cndmask_b32_e64 v77, v243, v77, s[6:7]
	v_cndmask_b32_e64 v76, v243, v76, s[6:7]
	v_cndmask_b32_e64 v75, v243, v75, s[6:7]
	v_cndmask_b32_e64 v74, v243, v74, s[6:7]
	v_cndmask_b32_e64 v73, v243, v73, s[6:7]
	v_cndmask_b32_e64 v72, v243, v72, s[6:7]
	v_cndmask_b32_e64 v71, v243, v71, s[6:7]
	v_cndmask_b32_e64 v70, v243, v70, s[6:7]
	v_cndmask_b32_e64 v69, v243, v69, s[6:7]
	v_cndmask_b32_e64 v68, v243, v68, s[6:7]
	v_cndmask_b32_e64 v67, v243, v67, s[6:7]
	v_cndmask_b32_e64 v66, v243, v66, s[6:7]
	s_waitcnt lgkmcnt(0)
	s_barrier
	ds_read_b128 v[82:85], v213 offset:0
	ds_read_b128 v[178:181], v213 offset:0x2000
	ds_read_b128 v[182:185], v218 offset:0
	ds_read_b128 v[186:189], v218 offset:0x2000
	ds_read_b128 v[192:195], v219 offset:0
	ds_read_b128 v[244:247], v219 offset:0x2000
	s_waitcnt lgkmcnt(4)
	s_nop 0
	v_mfma_f32_32x32x16_bf16 v[98:113], v[82:85], v[142:145], v[66:81]
	v_mfma_f32_32x32x16_bf16 v[82:97], v[178:181], v[142:145], v[66:81]
	ds_read_b128 v[178:181], v220 offset:0
	ds_read_b128 v[248:251], v220 offset:0x2000
	s_waitcnt lgkmcnt(4)
	v_mfma_f32_32x32x16_bf16 v[98:113], v[182:185], v[138:141], v[98:113]
	v_mfma_f32_32x32x16_bf16 v[82:97], v[186:189], v[138:141], v[82:97]
	ds_read_b128 v[182:185], v221 offset:0
	ds_read_b128 v[186:189], v221 offset:0x2000
	s_waitcnt lgkmcnt(4)
	v_mfma_f32_32x32x16_bf16 v[98:113], v[192:195], v[134:137], v[98:113]
	v_add_f32_e32 v192, v148, v146
	v_add_f32_e32 v193, v175, v177
	v_add_f32_e32 v194, v149, v147
	v_add_f32_e32 v195, v174, v176
	v_add_f32_e32 v192, v150, v192
	v_add_f32_e32 v193, v173, v193
	v_add_f32_e32 v194, v151, v194
	v_mfma_f32_32x32x16_bf16 v[82:97], v[244:247], v[134:137], v[82:97]
	v_add_f32_e32 v195, v172, v195
	v_add_f32_e32 v244, v152, v192
	v_add_f32_e32 v245, v171, v193
	v_add_f32_e32 v246, v153, v194
	v_add_f32_e32 v247, v170, v195
	ds_read_b128 v[192:195], v223 offset:0
	ds_read_b128 v[202:205], v223 offset:0x2000
	s_waitcnt lgkmcnt(4)
	v_mfma_f32_32x32x16_bf16 v[98:113], v[178:181], v[130:133], v[98:113]
	v_add_f32_e32 v178, v154, v244
	v_add_f32_e32 v179, v169, v245
	v_add_f32_e32 v180, v155, v246
	v_add_f32_e32 v181, v168, v247
	v_add_f32_e32 v178, v156, v178
	v_add_f32_e32 v179, v167, v179
	v_add_f32_e32 v180, v157, v180
	v_mfma_f32_32x32x16_bf16 v[82:97], v[248:251], v[130:133], v[82:97]
	v_add_f32_e32 v181, v166, v181
	v_add_f32_e32 v178, v158, v178
	v_add_f32_e32 v179, v165, v179
	v_add_f32_e32 v180, v159, v180
	v_add_f32_e32 v181, v164, v181
	v_add_f32_e32 v244, v160, v178
	v_add_f32_e32 v245, v163, v179
	v_add_f32_e32 v250, v161, v180
	v_add_f32_e32 v251, v162, v181
	ds_read_b128 v[178:181], v224 offset:0
	ds_read_b128 v[246:249], v224 offset:0x2000
	s_waitcnt lgkmcnt(4)
	v_mfma_f32_32x32x16_bf16 v[98:113], v[182:185], v[126:129], v[98:113]
	v_add_f32_e32 v182, v245, v244
	v_add_f32_e32 v183, v251, v250
	v_add_f32_e32 v244, v183, v182
	v_mov_b32_e32 v245, v244
	v_cvt_pk_bf16_f32 v146, v146, v177
	v_cvt_pk_bf16_f32 v147, v147, v176
	v_cvt_pk_bf16_f32 v148, v148, v175
	v_mfma_f32_32x32x16_bf16 v[82:97], v[186:189], v[126:129], v[82:97]
	v_cvt_pk_bf16_f32 v149, v149, v174
	s_nop 0
	v_permlane32_swap_b32_e32 v244, v245
	v_permlane32_swap_b32_e32 v146, v148
	v_permlane32_swap_b32_e32 v147, v149
	ds_read_b128 v[174:177], v225 offset:0
	ds_read_b128 v[182:185], v225 offset:0x2000
	s_waitcnt lgkmcnt(4)
	v_mfma_f32_32x32x16_bf16 v[98:113], v[192:195], v[122:125], v[98:113]
	v_cvt_pk_bf16_f32 v150, v150, v173
	v_cvt_pk_bf16_f32 v151, v151, v172
	v_cvt_pk_bf16_f32 v152, v152, v171
	v_cvt_pk_bf16_f32 v153, v153, v170
	s_nop 0
	v_permlane32_swap_b32_e32 v150, v152
	v_mfma_f32_32x32x16_bf16 v[82:97], v[202:205], v[122:125], v[82:97]
	v_permlane32_swap_b32_e32 v151, v153
	s_waitcnt lgkmcnt(2)
	v_mfma_f32_32x32x16_bf16 v[98:113], v[178:181], v[118:121], v[98:113]
	v_cvt_pk_bf16_f32 v154, v154, v169
	v_cvt_pk_bf16_f32 v155, v155, v168
	v_cvt_pk_bf16_f32 v156, v156, v167
	v_cvt_pk_bf16_f32 v157, v157, v166
	s_nop 0
	v_permlane32_swap_b32_e32 v154, v156
	v_mfma_f32_32x32x16_bf16 v[82:97], v[246:249], v[118:121], v[82:97]
	v_permlane32_swap_b32_e32 v155, v157
	s_waitcnt lgkmcnt(0)
	v_mfma_f32_32x32x16_bf16 v[98:113], v[174:177], v[114:117], v[98:113]
	v_cvt_pk_bf16_f32 v158, v158, v165
	v_cvt_pk_bf16_f32 v159, v159, v164
	v_cvt_pk_bf16_f32 v160, v160, v163
	v_cvt_pk_bf16_f32 v161, v161, v162
	s_nop 0
	v_permlane32_swap_b32_e32 v158, v160
	v_mfma_f32_32x32x16_bf16 v[82:97], v[182:185], v[114:117], v[82:97]
	v_permlane32_swap_b32_e32 v159, v161
	v_add_u32_e32 v170, 0x80, v238
	v_add_u32_e32 v172, 0xa0, v238
	v_mad_i64_i32 v[162:163], s[46:47], v170, s55, v[198:199]
	v_mad_i64_i32 v[166:167], s[46:47], v172, s55, v[198:199]
	v_mad_i64_i32 v[170:171], s[46:47], v170, s55, v[200:201]
	v_mad_i64_i32 v[174:175], s[46:47], v172, s55, v[200:201]
	global_load_dwordx4 v[162:165], v[162:163], off
	s_nop 0
	global_load_dwordx4 v[166:169], v[166:167], off
	s_nop 0
	global_load_dwordx4 v[170:173], v[170:171], off
	s_nop 0
	global_load_dwordx4 v[174:177], v[174:175], off
	s_and_b64 vcc, exec, s[8:9]
	s_cbranch_vccnz .LBB0_495
	ds_read2_b32 v[178:179], v236 offset0:64 offset1:65
	ds_read2_b32 v[180:181], v236 offset0:66 offset1:67
	ds_read2_b32 v[182:183], v236 offset0:72 offset1:73
	ds_read2_b32 v[184:185], v236 offset0:74 offset1:75
	ds_read2_b32 v[186:187], v236 offset0:80 offset1:81
	ds_read2_b32 v[188:189], v236 offset0:82 offset1:83
	ds_read2_b32 v[192:193], v236 offset0:88 offset1:89
	ds_read2_b32 v[194:195], v236 offset0:90 offset1:91
	ds_read2_b32 v[202:203], v236 offset0:96 offset1:97
	ds_read2_b32 v[204:205], v236 offset0:98 offset1:99
	ds_read2_b32 v[246:247], v236 offset0:104 offset1:105
	ds_read2_b32 v[248:249], v236 offset0:106 offset1:107
	s_waitcnt lgkmcnt(11)
	v_add_f32_e32 v98, v98, v178
	v_add_f32_e32 v99, v99, v179
	s_waitcnt lgkmcnt(5)
	v_add_f32_e32 v110, v110, v192
	v_add_f32_e32 v111, v111, v193
	v_add_f32_e32 v108, v108, v188
	v_add_f32_e32 v109, v109, v189
	v_add_f32_e32 v106, v106, v186
	v_add_f32_e32 v107, v107, v187
	ds_read2_b32 v[178:179], v236 offset0:112 offset1:113
	ds_read2_b32 v[186:187], v236 offset0:114 offset1:115
	ds_read2_b32 v[188:189], v236 offset0:120 offset1:121
	ds_read2_b32 v[192:193], v236 offset0:122 offset1:123
	s_waitcnt lgkmcnt(8)
	v_add_f32_e32 v112, v112, v194
	v_add_f32_e32 v113, v113, v195
	v_add_f32_e32 v104, v104, v184
	v_add_f32_e32 v105, v105, v185
	v_add_f32_e32 v102, v102, v182
	v_add_f32_e32 v103, v103, v183
	v_add_f32_e32 v100, v100, v180
	v_add_f32_e32 v101, v101, v181
	s_waitcnt lgkmcnt(7)
	v_add_f32_e32 v82, v82, v202
	v_add_f32_e32 v83, v83, v203
	s_waitcnt lgkmcnt(0)
	v_add_f32_e32 v96, v96, v192
	v_add_f32_e32 v97, v97, v193
	v_add_f32_e32 v94, v94, v188
	v_add_f32_e32 v95, v95, v189
	v_add_f32_e32 v92, v92, v186
	v_add_f32_e32 v93, v93, v187
	v_add_f32_e32 v90, v90, v178
	v_add_f32_e32 v91, v91, v179
	v_add_f32_e32 v88, v88, v248
	v_add_f32_e32 v89, v89, v249
	v_add_f32_e32 v86, v86, v246
	v_add_f32_e32 v87, v87, v247
	v_add_f32_e32 v84, v84, v204
	v_add_f32_e32 v85, v85, v205
